# mlstm2 state update: K^T fragments via ds_read_b64_tr_b16 (16 transposing reads replace 64 ds_read_u16 + permutes), double-buffered operand reads
# speedup vs baseline: 1.0383x; 1.0036x over previous
; __device__ __forceinline__ u16 f2bf(float f) { return (u16)(pk2(f, 0.f) & 0xffffu); }
; #define MFMA16(a, b, c) __builtin_amdgcn_mfma_f32_16x16x32_bf16((a), (b), (c), 0, 0, 0)
; __device__ void mlstm2_phase(const Params& p, unsigned char* smem) {
;     ...
;             for (int ks = 0; ks < 8; ++ks)
; #pragma unroll
;                 for (int nt = 0; nt < 3; ++nt) { const bf16x8 cf = *(const bf16x8*)(Ct + (16 * nt + l15) * 264 + 32 * ks + 8 * lq); oc[nt] = MFMA16(qf[ks], cf, oc[nt]); }
; #pragma unroll
;             for (int r = 0; r < 4; ++r) { const int t = 16 * wave + 4 * lq + r; const float Rf = gR[t], E = gE[t], F = gF[t];
;                 float den = Rf * oi[2][r] + E * oc[2][r]; den = __shfl(den, lane & 48);
;                 const float inv = 1.0f / fmaxf(fabsf(den), F);
; #pragma unroll
;                 for (int nt = 0; nt < 2; ++nt) Hm[(size_t)(row0 + t) * 2048 + 256 * h + 32 * sl + 16 * nt + l15] = f2bf((Rf * oi[nt][r] + E * oc[nt][r]) * inv); }
.LBB0_422:
	v_add_u32_e32 v82, v124, v150
	ds_read_b128 v[70:73], v82
	ds_read_b128 v[74:77], v219
	ds_read_b128 v[78:81], v219 offset:8448
	s_waitcnt lgkmcnt(2)
	v_mfma_f32_16x16x32_bf16 v[70:73], v[54:57], v[70:73], 0
	s_waitcnt lgkmcnt(1)
	v_mfma_f32_16x16x32_bf16 v[74:77], v[54:57], v[74:77], 0
	s_waitcnt lgkmcnt(0)
	v_mfma_f32_16x16x32_bf16 v[54:57], v[54:57], v[78:81], 0
	ds_read_b128 v[78:81], v82 offset:64
	s_waitcnt lgkmcnt(0)
	v_mfma_f32_16x16x32_bf16 v[70:73], v[50:53], v[78:81], v[70:73]
	ds_read_b128 v[78:81], v219 offset:64
	s_waitcnt lgkmcnt(0)
	v_mfma_f32_16x16x32_bf16 v[74:77], v[50:53], v[78:81], v[74:77]
	ds_read_b128 v[78:81], v219 offset:8512
	s_waitcnt lgkmcnt(0)
	v_mfma_f32_16x16x32_bf16 v[50:53], v[50:53], v[78:81], v[54:57]
	s_nop 2
	ds_read_b128 v[54:57], v82 offset:128
	s_waitcnt lgkmcnt(0)
	v_mfma_f32_16x16x32_bf16 v[54:57], v[46:49], v[54:57], v[70:73]
	s_nop 2
	ds_read_b128 v[70:73], v219 offset:128
	s_waitcnt lgkmcnt(0)
	v_mfma_f32_16x16x32_bf16 v[70:73], v[46:49], v[70:73], v[74:77]
	s_nop 2
	ds_read_b128 v[74:77], v219 offset:8576
	s_waitcnt lgkmcnt(0)
	v_mfma_f32_16x16x32_bf16 v[46:49], v[46:49], v[74:77], v[50:53]
	s_nop 2
	ds_read_b128 v[50:53], v82 offset:192
	s_waitcnt lgkmcnt(0)
	v_mfma_f32_16x16x32_bf16 v[50:53], v[42:45], v[50:53], v[54:57]
	s_nop 2
	ds_read_b128 v[54:57], v219 offset:192
	s_waitcnt lgkmcnt(0)
	v_mfma_f32_16x16x32_bf16 v[54:57], v[42:45], v[54:57], v[70:73]
	s_nop 2
	ds_read_b128 v[70:73], v219 offset:8640
	s_waitcnt lgkmcnt(0)
	v_mfma_f32_16x16x32_bf16 v[42:45], v[42:45], v[70:73], v[46:49]
	s_nop 2
	ds_read_b128 v[46:49], v82 offset:256
	s_waitcnt lgkmcnt(0)
	v_mfma_f32_16x16x32_bf16 v[46:49], v[38:41], v[46:49], v[50:53]
	s_nop 2
	ds_read_b128 v[50:53], v219 offset:256
	s_waitcnt lgkmcnt(0)
	v_mfma_f32_16x16x32_bf16 v[50:53], v[38:41], v[50:53], v[54:57]
	s_nop 2
	ds_read_b128 v[54:57], v219 offset:8704
	s_waitcnt lgkmcnt(0)
	v_mfma_f32_16x16x32_bf16 v[38:41], v[38:41], v[54:57], v[42:45]
	s_nop 2
	ds_read_b128 v[42:45], v82 offset:320
	s_waitcnt lgkmcnt(0)
	v_mfma_f32_16x16x32_bf16 v[42:45], v[34:37], v[42:45], v[46:49]
	s_nop 2
	ds_read_b128 v[46:49], v219 offset:320
	s_waitcnt lgkmcnt(0)
	v_mfma_f32_16x16x32_bf16 v[46:49], v[34:37], v[46:49], v[50:53]
	s_nop 2
	ds_read_b128 v[50:53], v219 offset:8768
	s_waitcnt lgkmcnt(0)
	v_mfma_f32_16x16x32_bf16 v[34:37], v[34:37], v[50:53], v[38:41]
	s_nop 2
	ds_read_b128 v[38:41], v82 offset:384
	s_waitcnt lgkmcnt(0)
	v_mfma_f32_16x16x32_bf16 v[38:41], v[30:33], v[38:41], v[42:45]
	s_nop 2
	ds_read_b128 v[42:45], v219 offset:384
	s_waitcnt lgkmcnt(0)
	v_mfma_f32_16x16x32_bf16 v[42:45], v[30:33], v[42:45], v[46:49]
	s_nop 2
	ds_read_b128 v[46:49], v219 offset:8832
	s_waitcnt lgkmcnt(0)
	v_mfma_f32_16x16x32_bf16 v[46:49], v[30:33], v[46:49], v[34:37]
	ds_read_b128 v[30:33], v82 offset:448
	s_waitcnt lgkmcnt(0)
	v_mfma_f32_16x16x32_bf16 v[34:37], v[26:29], v[30:33], v[38:41]
	ds_read_b128 v[30:33], v219 offset:448
	s_nop 1
	ds_read_b128 v[38:41], v219 offset:8896
	s_waitcnt lgkmcnt(1)
	v_mfma_f32_16x16x32_bf16 v[30:33], v[26:29], v[30:33], v[42:45]
	s_waitcnt lgkmcnt(0)
	v_mfma_f32_16x16x32_bf16 v[26:29], v[26:29], v[38:41], v[46:49]
	ds_read_b32 v39, v197
	ds_read_b32 v44, v198
	ds_read_b32 v40, v199
	v_and_or_b32 v38, v226, 64, v121
	v_lshlrev_b32_e32 v38, 2, v38
	s_waitcnt lgkmcnt(1)
	s_nop 1
	v_mul_f32_e32 v26, v26, v44
	v_fmac_f32_e32 v26, v66, v39
	ds_bpermute_b32 v26, v38, v26
	s_waitcnt lgkmcnt(1)
	v_max_f32_e32 v40, v40, v40
	v_mul_f32_e32 v34, v34, v44
	v_mul_f32_e32 v30, v30, v44
	v_fmac_f32_e32 v34, v62, v39
	s_waitcnt lgkmcnt(0)
	v_max_f32_e64 v26, |v26|, |v26|
	v_max_f32_e32 v26, v26, v40
	v_div_scale_f32 v40, s[26:27], v26, v26, 1.0
	v_rcp_f32_e32 v41, v40
	v_fmac_f32_e32 v30, v58, v39
	v_fma_f32 v42, -v40, v41, 1.0
	v_fmac_f32_e32 v41, v42, v41
	v_div_scale_f32 v42, vcc, 1.0, v26, 1.0
	v_mul_f32_e32 v43, v42, v41
	v_fma_f32 v45, -v40, v43, v42
	v_fmac_f32_e32 v43, v45, v41
	v_fma_f32 v40, -v40, v43, v42
	v_div_fmas_f32 v40, v40, v41, v43
	v_div_fixup_f32 v26, v40, v26, 1.0
	v_add_u32_e32 v40, s79, v230
	v_ashrrev_i32_e32 v41, 31, v40
	v_lshlrev_b64 v[42:43], 12, v[40:41]
	v_lshl_add_u64 v[42:43], v[108:109], 0, v[42:43]
	v_mul_f32_e32 v34, v34, v26
	v_mul_f32_e32 v26, v30, v26
	v_cvt_pk_bf16_f32 v34, v34, v93
	global_store_short v[42:43], v34, off
	v_cvt_pk_bf16_f32 v26, v26, v93
	global_store_short v[42:43], v26, off offset:32
	ds_read_b32 v30, v200
	ds_read_b32 v34, v201
	ds_read_b32 v26, v202
	s_addk_i32 s79, 0x80
	s_cmpk_eq_i32 s79, 0x1000
	s_waitcnt lgkmcnt(1)
	v_mul_f32_e32 v27, v27, v34
	v_fmac_f32_e32 v27, v67, v30
	ds_bpermute_b32 v27, v38, v27
	s_waitcnt lgkmcnt(1)
	v_max_f32_e32 v26, v26, v26
	v_mul_f32_e32 v35, v35, v34
	v_mul_f32_e32 v31, v31, v34
	v_fmac_f32_e32 v35, v63, v30
	s_waitcnt lgkmcnt(0)
	v_max_f32_e64 v27, |v27|, |v27|
	v_max_f32_e32 v26, v27, v26
	v_div_scale_f32 v27, s[26:27], v26, v26, 1.0
	v_rcp_f32_e32 v39, v27
	v_fmac_f32_e32 v31, v59, v30
	v_fma_f32 v41, -v27, v39, 1.0
	v_fmac_f32_e32 v39, v41, v39
	v_div_scale_f32 v41, vcc, 1.0, v26, 1.0
	v_mul_f32_e32 v42, v41, v39
	v_fma_f32 v43, -v27, v42, v41
	v_fmac_f32_e32 v42, v43, v39
	v_fma_f32 v27, -v27, v42, v41
	v_div_fmas_f32 v27, v27, v39, v42
	v_div_fixup_f32 v39, v27, v26, 1.0
	v_add_u32_e32 v26, 1, v40
	v_ashrrev_i32_e32 v27, 31, v26
	v_lshlrev_b64 v[26:27], 12, v[26:27]
	v_lshl_add_u64 v[26:27], v[108:109], 0, v[26:27]
	v_mul_f32_e32 v35, v35, v39
	v_mul_f32_e32 v30, v31, v39
	v_cvt_pk_bf16_f32 v35, v35, v93
	global_store_short v[26:27], v35, off
	v_cvt_pk_bf16_f32 v30, v30, v93
	global_store_short v[26:27], v30, off offset:32
	ds_read_b32 v30, v203
	ds_read_b32 v31, v204
	ds_read_b32 v26, v205
	s_waitcnt lgkmcnt(1)
; __device__ __forceinline__ u16 f2bf(float f) { return (u16)(pk2(f, 0.f) & 0xffffu); }
; #define MFMA16(a, b, c) __builtin_amdgcn_mfma_f32_16x16x32_bf16((a), (b), (c), 0, 0, 0)
; __device__ void mlstm2_phase(const Params& p, unsigned char* smem) {
;     ...
;             for (int r = 0; r < 4; ++r) { const int t = 16 * wave + 4 * lq + r; const float Rf = gR[t], E = gE[t], F = gF[t];
;                 float den = Rf * oi[2][r] + E * oc[2][r]; den = __shfl(den, lane & 48);
;                 const float inv = 1.0f / fmaxf(fabsf(den), F);
; #pragma unroll
;                 for (int nt = 0; nt < 2; ++nt) Hm[(size_t)(row0 + t) * 2048 + 256 * h + 32 * sl + 16 * nt + l15] = f2bf((Rf * oi[nt][r] + E * oc[nt][r]) * inv); }
;             { const float decay = gS[0];
; #pragma unroll
;               for (int a = 0; a < 3; ++a)
; #pragma unroll
;                 for (int c = 0; c < 2; ++c) accC[a][c] = accC[a][c] * decay; }
; #pragma unroll
;             for (int kk = 0; kk < 4; ++kk) {
;                 bf16x8 ktf[2];
; #pragma unroll
;                 for (int ntk = 0; ntk < 2; ++ntk) { const int dk = 32 * wave + 16 * ntk + l15;
; #pragma unroll
;                     for (int j = 0; j < 8; ++j) ktf[ntk][j] = (short)Ks[(32 * kk + 8 * lq + j) * 264 + dk]; }
; #pragma unroll
;                 for (int mt = 0; mt < 3; ++mt) { const bf16x8 vwf = *(const bf16x8*)(Vwt + (16 * mt + l15) * 136 + 32 * kk + 8 * lq);
; #pragma unroll
;                     for (int ntk = 0; ntk < 2; ++ntk) accC[mt][ntk] = MFMA16(vwf, ktf[ntk], accC[mt][ntk]); }
;             }
	v_mul_f32_e32 v27, v28, v31
	v_fmac_f32_e32 v27, v68, v30
	ds_bpermute_b32 v27, v38, v27
	s_waitcnt lgkmcnt(1)
	v_max_f32_e32 v26, v26, v26
	s_waitcnt lgkmcnt(0)
	v_max_f32_e64 v27, |v27|, |v27|
	v_max_f32_e32 v26, v27, v26
	v_div_scale_f32 v27, s[26:27], v26, v26, 1.0
	v_rcp_f32_e32 v28, v27
	s_nop 0
	v_fma_f32 v34, -v27, v28, 1.0
	v_fmac_f32_e32 v28, v34, v28
	v_div_scale_f32 v34, vcc, 1.0, v26, 1.0
	v_mul_f32_e32 v35, v34, v28
	v_fma_f32 v39, -v27, v35, v34
	v_fmac_f32_e32 v35, v39, v28
	v_fma_f32 v27, -v27, v35, v34
	v_div_fmas_f32 v27, v27, v28, v35
	v_div_fixup_f32 v28, v27, v26, 1.0
	v_add_u32_e32 v26, 2, v40
	v_ashrrev_i32_e32 v27, 31, v26
	v_mul_f32_e32 v34, v36, v31
	v_mul_f32_e32 v31, v32, v31
	v_lshlrev_b64 v[26:27], 12, v[26:27]
	v_fmac_f32_e32 v34, v64, v30
	v_fmac_f32_e32 v31, v60, v30
	v_lshl_add_u64 v[26:27], v[108:109], 0, v[26:27]
	v_mul_f32_e32 v34, v34, v28
	v_mul_f32_e32 v28, v31, v28
	v_cvt_pk_bf16_f32 v34, v34, v93
	global_store_short v[26:27], v34, off
	v_cvt_pk_bf16_f32 v28, v28, v93
	global_store_short v[26:27], v28, off offset:32
	ds_read_b32 v28, v206
	ds_read_b32 v30, v207
	ds_read_b32 v26, v208
	s_waitcnt lgkmcnt(1)
	v_mul_f32_e32 v27, v29, v30
	v_fmac_f32_e32 v27, v69, v28
	ds_bpermute_b32 v27, v38, v27
	s_waitcnt lgkmcnt(1)
	v_max_f32_e32 v26, v26, v26
	s_waitcnt lgkmcnt(0)
	v_max_f32_e64 v27, |v27|, |v27|
	v_max_f32_e32 v26, v27, v26
	v_div_scale_f32 v27, s[26:27], v26, v26, 1.0
	v_rcp_f32_e32 v29, v27
	s_nop 0
	v_fma_f32 v31, -v27, v29, 1.0
	v_fmac_f32_e32 v29, v31, v29
	v_div_scale_f32 v31, vcc, 1.0, v26, 1.0
	v_mul_f32_e32 v32, v31, v29
	v_fma_f32 v34, -v27, v32, v31
	v_fmac_f32_e32 v32, v34, v29
	v_fma_f32 v27, -v27, v32, v31
	v_div_fmas_f32 v27, v27, v29, v32
	v_div_fixup_f32 v29, v27, v26, 1.0
	v_add_u32_e32 v26, 3, v40
	v_ashrrev_i32_e32 v27, 31, v26
	v_mul_f32_e32 v31, v37, v30
	v_mul_f32_e32 v30, v33, v30
	v_lshlrev_b64 v[26:27], 12, v[26:27]
	v_fmac_f32_e32 v31, v65, v28
	v_fmac_f32_e32 v30, v61, v28
	v_lshl_add_u64 v[26:27], v[108:109], 0, v[26:27]
	v_mul_f32_e32 v31, v31, v29
	v_mul_f32_e32 v28, v30, v29
	v_cvt_pk_bf16_f32 v31, v31, v93
	global_store_short v[26:27], v31, off
	v_cvt_pk_bf16_f32 v28, v28, v93
	global_store_short v[26:27], v28, off offset:32
	v_mov_b32_e32 v26, s91
	ds_read_b32 v34, v26
	v_and_b32_e32 v27, 15, v0
	v_lshrrev_b32_e32 v28, 2, v27
	v_and_b32_e32 v29, 3, v27
	v_lshlrev_b32_e32 v27, 1, v27
	v_sub_u32_e32 v27, v209, v27
	v_mul_u32_u24_e32 v28, 0x210, v28
	v_lshl_add_u32 v27, v29, 3, v27
	v_add_u32_e32 v27, v27, v28
	ds_read_b64_tr_b16 v[36:37], v27
	ds_read_b64_tr_b16 v[38:39], v27 offset:2112
	ds_read_b64_tr_b16 v[40:41], v27 offset:32
	ds_read_b64_tr_b16 v[42:43], v27 offset:2144
	ds_read_b128 v[44:47], v220
	ds_read_b128 v[48:51], v220 offset:4352
	ds_read_b128 v[52:55], v220 offset:8704
	ds_read_b64_tr_b16 v[56:57], v27 offset:16896
	ds_read_b64_tr_b16 v[58:59], v27 offset:19008
	ds_read_b64_tr_b16 v[60:61], v27 offset:16928
	ds_read_b64_tr_b16 v[62:63], v27 offset:19040
	ds_read_b128 v[64:67], v220 offset:64
	ds_read_b128 v[68:71], v220 offset:4416
	ds_read_b128 v[72:75], v220 offset:8768
	s_waitcnt lgkmcnt(14)
	v_pk_mul_f32 v[2:3], v[2:3], v[34:35] op_sel_hi:[1,0]
	v_pk_mul_f32 v[4:5], v[4:5], v[34:35] op_sel_hi:[1,0]
	v_pk_mul_f32 v[6:7], v[6:7], v[34:35] op_sel_hi:[1,0]
	v_pk_mul_f32 v[8:9], v[8:9], v[34:35] op_sel_hi:[1,0]
	v_pk_mul_f32 v[10:11], v[10:11], v[34:35] op_sel_hi:[1,0]
	v_pk_mul_f32 v[12:13], v[12:13], v[34:35] op_sel_hi:[1,0]
	v_pk_mul_f32 v[14:15], v[14:15], v[34:35] op_sel_hi:[1,0]
	v_pk_mul_f32 v[16:17], v[16:17], v[34:35] op_sel_hi:[1,0]
	v_pk_mul_f32 v[18:19], v[18:19], v[34:35] op_sel_hi:[1,0]
	v_pk_mul_f32 v[20:21], v[20:21], v[34:35] op_sel_hi:[1,0]
	v_pk_mul_f32 v[22:23], v[22:23], v[34:35] op_sel_hi:[1,0]
	v_pk_mul_f32 v[24:25], v[24:25], v[34:35] op_sel_hi:[1,0]
	s_waitcnt lgkmcnt(7)
	v_mfma_f32_16x16x32_bf16 v[2:5], v[44:47], v[36:39], v[2:5]
	v_mfma_f32_16x16x32_bf16 v[6:9], v[44:47], v[40:43], v[6:9]
	v_mfma_f32_16x16x32_bf16 v[10:13], v[48:51], v[36:39], v[10:13]
	v_mfma_f32_16x16x32_bf16 v[14:17], v[48:51], v[40:43], v[14:17]
	v_mfma_f32_16x16x32_bf16 v[18:21], v[52:55], v[36:39], v[18:21]
	v_mfma_f32_16x16x32_bf16 v[22:25], v[52:55], v[40:43], v[22:25]
	ds_read_b64_tr_b16 v[36:37], v27 offset:33792
	ds_read_b64_tr_b16 v[38:39], v27 offset:35904
	ds_read_b64_tr_b16 v[40:41], v27 offset:33824
	ds_read_b64_tr_b16 v[42:43], v27 offset:35936
	ds_read_b128 v[44:47], v220 offset:128
	ds_read_b128 v[48:51], v220 offset:4480
	ds_read_b128 v[52:55], v220 offset:8832
	s_waitcnt lgkmcnt(7)
	v_mfma_f32_16x16x32_bf16 v[2:5], v[64:67], v[56:59], v[2:5]
	v_mfma_f32_16x16x32_bf16 v[6:9], v[64:67], v[60:63], v[6:9]
	v_mfma_f32_16x16x32_bf16 v[10:13], v[68:71], v[56:59], v[10:13]
	v_mfma_f32_16x16x32_bf16 v[14:17], v[68:71], v[60:63], v[14:17]
	v_mfma_f32_16x16x32_bf16 v[18:21], v[72:75], v[56:59], v[18:21]
	v_mfma_f32_16x16x32_bf16 v[22:25], v[72:75], v[60:63], v[22:25]
	ds_read_b64_tr_b16 v[56:57], v27 offset:50688
	ds_read_b64_tr_b16 v[58:59], v27 offset:52800
	ds_read_b64_tr_b16 v[60:61], v27 offset:50720
	ds_read_b64_tr_b16 v[62:63], v27 offset:52832
	ds_read_b128 v[64:67], v220 offset:192
	ds_read_b128 v[68:71], v220 offset:4544
	ds_read_b128 v[72:75], v220 offset:8896
	s_waitcnt lgkmcnt(7)
	v_mfma_f32_16x16x32_bf16 v[2:5], v[44:47], v[36:39], v[2:5]
	v_mfma_f32_16x16x32_bf16 v[6:9], v[44:47], v[40:43], v[6:9]
	v_mfma_f32_16x16x32_bf16 v[10:13], v[48:51], v[36:39], v[10:13]
	v_mfma_f32_16x16x32_bf16 v[14:17], v[48:51], v[40:43], v[14:17]
	v_mfma_f32_16x16x32_bf16 v[18:21], v[52:55], v[36:39], v[18:21]
	v_mfma_f32_16x16x32_bf16 v[22:25], v[52:55], v[40:43], v[22:25]
	s_waitcnt lgkmcnt(0)
	v_mfma_f32_16x16x32_bf16 v[2:5], v[64:67], v[56:59], v[2:5]
	v_mfma_f32_16x16x32_bf16 v[6:9], v[64:67], v[60:63], v[6:9]
	v_mfma_f32_16x16x32_bf16 v[10:13], v[68:71], v[56:59], v[10:13]
	v_mfma_f32_16x16x32_bf16 v[14:17], v[68:71], v[60:63], v[14:17]
	v_mfma_f32_16x16x32_bf16 v[18:21], v[72:75], v[56:59], v[18:21]
	v_mfma_f32_16x16x32_bf16 v[22:25], v[72:75], v[60:63], v[22:25]
	s_barrier
; __device__ __forceinline__ u16 f2bf(float f) { return (u16)(pk2(f, 0.f) & 0xffffu); }
; __device__ void mlstm2_phase(const Params& p, unsigned char* smem) {
;     ...
;             __syncthreads();
; #pragma unroll
;             for (int mt = 0; mt < 3; ++mt)
; #pragma unroll
;                 for (int ntk = 0; ntk < 2; ++ntk)
; #pragma unroll
;                     for (int r = 0; r < 4; ++r) Ct[(16 * mt + 4 * lq + r) * 264 + 32 * wave + 16 * ntk + l15] = f2bf(accC[mt][ntk][r]);
	s_nop 7
	s_nop 3
	v_cvt_pk_bf16_f32 v26, v2, v3
	ds_write_b16 v221, v26
	ds_write_b16_d16_hi v221, v26 offset:528
	v_cvt_pk_bf16_f32 v26, v4, v5
	ds_write_b16 v221, v26 offset:1056
	ds_write_b16_d16_hi v221, v26 offset:1584
	v_cvt_pk_bf16_f32 v26, v6, v7
	ds_write_b16 v221, v26 offset:32
	ds_write_b16_d16_hi v221, v26 offset:560
	v_cvt_pk_bf16_f32 v26, v8, v9
	ds_write_b16 v221, v26 offset:1088
	ds_write_b16_d16_hi v221, v26 offset:1616
	v_cvt_pk_bf16_f32 v26, v10, v11
	ds_write_b16 v221, v26 offset:8448
	ds_write_b16_d16_hi v221, v26 offset:8976
	v_cvt_pk_bf16_f32 v26, v12, v13
	ds_write_b16 v221, v26 offset:9504
	ds_write_b16_d16_hi v221, v26 offset:10032
	v_cvt_pk_bf16_f32 v26, v14, v15
	ds_write_b16 v221, v26 offset:8480
	ds_write_b16_d16_hi v221, v26 offset:9008
	v_cvt_pk_bf16_f32 v26, v16, v17
	ds_write_b16 v221, v26 offset:9536
	ds_write_b16_d16_hi v221, v26 offset:10064
	v_cvt_pk_bf16_f32 v26, v18, v19
	ds_write_b16 v221, v26 offset:16896
	ds_write_b16_d16_hi v221, v26 offset:17424
	v_cvt_pk_bf16_f32 v26, v20, v21
	ds_write_b16 v221, v26 offset:17952
	ds_write_b16_d16_hi v221, v26 offset:18480
	v_cvt_pk_bf16_f32 v26, v22, v23
	ds_write_b16 v221, v26 offset:16928
	ds_write_b16_d16_hi v221, v26 offset:17456
	v_cvt_pk_bf16_f32 v26, v24, v25
	ds_write_b16 v221, v26 offset:17984
	ds_write_b16_d16_hi v221, v26 offset:18512
	s_cbranch_scc1 .LBB0_414
